# phase 3: stick-breaking items take query tiles in reverse of FOX; conversion items dealt dynamically (atomic counter, chunks of 4) after the static items
# speedup vs baseline: 1.0102x; 1.0102x over previous
; DI void phase_attn1(const Params& p, int L, char* smem) {
;     ...
;   for (int it = blockIdx.x; it < 1792 + extra; it += gridDim.x) {
;     if (it < 512) attn_item<2>(p, it, smem);
;     else if (it < 1024) nsacmp_item(p, L, it - 512, smem);
;     else if (it < 1536) attn_item<0>(p, it - 1024, smem);
;     else if (it < 1792) mlaprep_item(p, L, it - 1536, smem);
;     else conv_item_C(p, L, it - 1792, smem);
;   }
.LBB0_150:
	v_readlane_b32 s33, v255, 61
	s_nop 3
	s_cmpk_ge_i32 s33, 0x600
	s_cbranch_scc1 .Lq_dyn
	v_readlane_b32 s2, v254, 38
	v_readlane_b32 s3, v254, 39
	s_nop 3
	s_load_dword s2, s[2:3], 0x0
	s_waitcnt lgkmcnt(0)
	s_add_i32 s33, s2, s33
	s_branch .LBB0_151
.Lq_dyn:
	s_cmpk_le_i32 s60, 0x800
	s_cbranch_scc1 .LBB0_484
	s_cmpk_lt_i32 s33, 0x800
	s_cbranch_scc1 .Lq_fetch
	s_and_b32 s2, s33, 3
	s_cmp_eq_u32 s2, 3
	s_cbranch_scc1 .Lq_fetch
	s_add_i32 s33, s33, 1
	s_branch .LBB0_151
.Lq_fetch:
	s_waitcnt vmcnt(0) lgkmcnt(0)
	s_barrier
	v_readfirstlane_b32 s2, v224
	s_nop 3
	s_cmp_lt_u32 s2, 64
	s_cbranch_scc0 .Lq_wait
	v_readlane_b32 s98, v254, 38
	v_readlane_b32 s99, v254, 39
	v_readlane_b32 s2, v255, 26
	s_nop 3
	s_sub_u32 s98, s98, 0x288
	s_subb_u32 s99, s99, 0
	s_load_dwordx2 s[98:99], s[98:99], 0x250
	s_lshl_b32 s2, s2, 8
	s_addk_i32 s2, 0x2000
	s_waitcnt lgkmcnt(0)
	s_add_u32 s98, s98, s2
	s_addc_u32 s99, s99, 0
	s_mov_b64 vcc, exec
	s_mov_b64 exec, 1
	v_mov_b32_e32 v0, 0
	v_mov_b32_e32 v1, 1
	s_nop 4
	global_atomic_add v1, v0, v1, s[98:99] sc0
	s_waitcnt vmcnt(0)
	v_mov_b32_e32 v0, 0xe000
	ds_write_b32 v0, v1
	s_waitcnt lgkmcnt(0)
	s_mov_b64 exec, vcc
.Lq_wait:
	s_barrier
	v_mov_b32_e32 v0, 0xe000
	ds_read_b32 v0, v0
	s_waitcnt lgkmcnt(0)
	v_readfirstlane_b32 s33, v0
	s_nop 3
	s_lshl_b32 s33, s33, 2
	s_addk_i32 s33, 0x800
	s_cmp_ge_i32 s33, s60
	s_cbranch_scc1 .LBB0_484
	s_branch .LBB0_151

; DI int TID() { int t = threadIdx.x; asm volatile("" : "+v"(t)); return t; }
; template <int MODE>
; DI void attn_run(const bfu* __restrict__ Qp, const bfu* __restrict__ Kp, const bfu* __restrict__ Vtp, int qt,
;                  f32x16 (&o)[2], const float* __restrict__ cump, unsigned sel, unsigned blockmask, char* smem) {
;     ...
;   const int tid = TID(), lane = tid & 63, w = tid >> 6, r = lane & 31, hh = lane >> 5;
;   const int q0 = qt * 128;
;   const int t = q0 + w * 32 + r;
;   const int tw_min = q0 + w * 32, tw_max = tw_min + 31;
;   bf16x8 qf[NKS];
; #pragma unroll
;   for (int ks = 0; ks < NKS; ++ks) qf[ks] = *(const bf16x8*)(Qp + (size_t)t * DK + ks * 16 + hh * 8);
;   float cumq = 0.f;
;   if (MODE == 2) cumq = cump[t];
;   bf16x8 U[2];
;   if (MODE == 0) {
; #pragma unroll
;     for (int s2 = 0; s2 < 2; ++s2)
; #pragma unroll
;       for (int j = 0; j < 8; ++j) { int kk = 16 * s2 + 8 * (j >> 2) + 4 * hh + (j & 3); U[s2][j] = (kk > r) ? (short)0x3F80 : (short)0; }
;   }
; #pragma unroll
;   for (int dt = 0; dt < 2; ++dt)
; #pragma unroll
;     for (int i = 0; i < 16; ++i) o[dt][i] = 0.f;
;   float m = -INFINITY, l = 0.f, carry = 0.f;
;   int kt_lo = 0, kt_hi = 2 * qt + 1;
;   if (MODE == 4) kt_lo = (2 * qt - 8) > 0 ? (2 * qt - 8) : 0;
;   int kt;
;   if (MODE == 0) kt = kt_hi;
;   else if (MODE == 3) { kt = kt_lo; while (kt <= kt_hi && !((blockmask >> kt) & 1u)) ++kt; }
;   else kt = kt_lo;
;   u32x4 rk[NKC], rv[2]; float rc = 0.f;
;     ...
;   if (kt <= kt_hi && kt >= 0) { ATT_LOAD(kt) }
; template <int MODE>
; DI void attn_item(const Params& p, int idx, char* smem) {
;   const int tid = TID(), lane = tid & 63, w = tid >> 6, r = lane & 31, hh = lane >> 5;
;   const int qt = 15 - (idx >> 5); const int bh = idx & 31, b = bh >> 2, h = bh & 3;
;   const int spos = qt * 128 + w * 32 + r;
;   const size_t t = (size_t)b * S + spos;
;   __syncthreads();
;   if (tid < 4) ((int*)(smem + AT_FLAGS))[tid] = 0;
;   f32x16 o[2];
;   if (MODE == 0) {
.LBB0_204:
	s_andn2_b64 vcc, exec, s[2:3]
	s_cbranch_vccnz .LBB0_216
	v_mov_b32_e32 v182, v224
	s_waitcnt vmcnt(63) expcnt(7) lgkmcnt(15)
	v_cmp_gt_i32_e32 vcc, 4, v182
	s_barrier
	s_and_saveexec_b64 s[2:3], vcc
	v_lshlrev_b32_e32 v0, 2, v182
	ds_write_b32 v0, v189 offset:22784
	s_or_b64 exec, exec, s[2:3]
	s_add_i32 s54, s33, 0xfffffc00
	s_lshr_b32 s2, s54, 5
	s_mov_b32 s8, s2
	v_mov_b32_e32 v8, v224
	s_lshl_b32 s12, s8, 7
	s_and_b32 s2, s33, 31
	v_ashrrev_i32_e32 v15, 6, v8
	v_and_b32_e32 v16, 31, v8
	v_lshl_add_u32 v17, v15, 5, s12
	s_lshl_b32 s2, s2, 18
	v_readlane_b32 s16, v254, 2
	v_or_b32_e32 v104, v17, v16
	v_readlane_b32 s17, v254, 3
	s_add_u32 s6, s16, s2
	v_ashrrev_i32_e32 v105, 31, v104
	s_addc_u32 s7, s17, 0
	v_bfe_u32 v2, v8, 5, 1
	v_lshlrev_b64 v[0:1], 7, v[104:105]
	v_lshl_add_u64 v[0:1], s[6:7], 0, v[0:1]
	v_lshlrev_b32_e32 v188, 4, v2
	v_lshlrev_b32_e32 v183, 2, v2
	v_lshl_add_u64 v[0:1], v[0:1], 0, v[188:189]
	v_cmp_gt_u32_e32 vcc, v183, v16
	global_load_dwordx4 v[64:67], v[0:1], off
	global_load_dwordx4 v[68:71], v[0:1], off offset:32
	global_load_dwordx4 v[72:75], v[0:1], off offset:64
	global_load_dwordx4 v[76:79], v[0:1], off offset:96
	v_cndmask_b32_e32 v0, 0, v231, vcc
	v_cmp_lt_u32_e32 vcc, v183, v16
	v_readlane_b32 s18, v254, 4
	v_readlane_b32 s19, v254, 5
	v_cndmask_b32_e64 v1, v231, 0, vcc
	s_waitcnt vmcnt(6)
	v_perm_b32 v80, v1, v0, s0
	v_or_b32_e32 v1, 2, v183
	v_or_b32_e32 v0, 3, v183
	v_cmp_gt_u32_e32 vcc, v1, v16
	s_add_u32 s4, s18, s2
	v_readlane_b32 s20, v254, 6
	v_cndmask_b32_e32 v1, 0, v231, vcc
	v_cmp_gt_u32_e32 vcc, v0, v16
	s_addc_u32 s5, s19, 0
	v_add_u32_e32 v6, 0x100, v8
	v_cndmask_b32_e32 v0, 0, v231, vcc
	v_perm_b32 v81, v0, v1, s0
	v_or_b32_e32 v1, 8, v183
	v_or_b32_e32 v0, 9, v183
	v_cmp_gt_u32_e32 vcc, v1, v16
	v_readlane_b32 s21, v254, 7
	s_add_u32 s2, s20, s2
	v_cndmask_b32_e32 v1, 0, v231, vcc
	v_cmp_gt_u32_e32 vcc, v0, v16
	v_lshlrev_b32_e32 v18, 3, v2
	v_ashrrev_i32_e32 v2, 31, v6
	v_cndmask_b32_e32 v0, 0, v231, vcc
	v_perm_b32 v82, v0, v1, s0
	v_or_b32_e32 v1, 10, v183
	v_or_b32_e32 v0, 11, v183
	v_cmp_gt_u32_e32 vcc, v1, v16
	s_addc_u32 s3, s21, 0
	s_lshl_b32 s95, s8, 1
	v_cndmask_b32_e32 v1, 0, v231, vcc
	v_cmp_gt_u32_e32 vcc, v0, v16
	v_lshrrev_b32_e32 v2, 29, v2
	s_or_b32 s94, s95, 1
	v_cndmask_b32_e32 v0, 0, v231, vcc
	v_perm_b32 v83, v0, v1, s0
	v_or_b32_e32 v0, 16, v183
	v_cmp_gt_u32_e32 vcc, v0, v16
	v_ashrrev_i32_e32 v0, 31, v8
	v_lshrrev_b32_e32 v0, 29, v0
	v_add_u32_e32 v2, v6, v2
	v_ashrrev_i32_e32 v4, 3, v8
	v_add_u32_e32 v0, v8, v0
	v_ashrrev_i32_e32 v185, 3, v2
	v_and_b32_e32 v2, -8, v2
	v_ashrrev_i32_e32 v5, 31, v4
	s_lshl_b32 s8, s94, 6
	s_lshl_b32 s6, s94, 7
	v_ashrrev_i32_e32 v184, 3, v0
	v_and_b32_e32 v0, -8, v0
	v_sub_u32_e32 v23, v6, v2
	v_lshlrev_b64 v[106:107], 12, v[4:5]
	v_ashrrev_i32_e32 v6, 3, v6
	s_add_u32 s6, s2, s6
	v_lshlrev_b32_e32 v5, 4, v8
	v_and_b32_e32 v14, 63, v8
	v_sub_u32_e32 v22, v8, v0
	v_ashrrev_i32_e32 v7, 31, v6
	s_addc_u32 s7, s3, 0
	v_and_b32_e32 v8, 0x70, v5
	v_mov_b32_e32 v9, v189
	v_lshlrev_b64 v[108:109], 12, v[6:7]
	v_lshl_add_u64 v[10:11], s[6:7], 0, v[8:9]
	v_lshl_add_u64 v[12:13], v[10:11], 0, v[108:109]
	v_lshl_add_u64 v[10:11], v[10:11], 0, v[106:107]
	global_load_dwordx4 v[88:91], v[12:13], off
	global_load_dwordx4 v[92:95], v[10:11], off
	v_add_u32_e32 v10, s8, v185
	v_lshlrev_b32_e32 v2, 3, v23
	v_ashrrev_i32_e32 v11, 31, v10
	v_add_u32_e32 v12, s8, v184
	v_lshlrev_b32_e32 v0, 3, v22
	v_ashrrev_i32_e32 v3, 31, v2
	v_lshlrev_b64 v[10:11], 7, v[10:11]
	v_ashrrev_i32_e32 v13, 31, v12
	v_ashrrev_i32_e32 v1, 31, v0
	v_lshl_add_u64 v[10:11], s[4:5], 0, v[10:11]
	v_lshlrev_b64 v[2:3], 1, v[2:3]
	v_lshlrev_b64 v[12:13], 7, v[12:13]
	v_lshl_add_u64 v[10:11], v[10:11], 0, v[2:3]
	v_lshl_add_u64 v[12:13], s[4:5], 0, v[12:13]
	v_lshlrev_b64 v[0:1], 1, v[0:1]
	v_lshl_add_u64 v[12:13], v[12:13], 0, v[0:1]
	global_load_dwordx4 v[96:99], v[10:11], off
	global_load_dwordx4 v[100:103], v[12:13], off
	v_or_b32_e32 v21, 17, v183
	v_cndmask_b32_e32 v19, 0, v231, vcc
	v_or_b32_e32 v20, 18, v183
	v_cmp_gt_u32_e32 vcc, v21, v16
	v_or_b32_e32 v11, 19, v183
	v_or_b32_e32 v10, 24, v183
	v_cndmask_b32_e32 v5, 0, v231, vcc
	v_cmp_gt_u32_e32 vcc, v20, v16
	v_or_b32_e32 v12, 26, v183
	v_or_b32_e32 v13, 25, v183
	v_cndmask_b32_e32 v7, 0, v231, vcc
	v_cmp_gt_u32_e32 vcc, v11, v16
	v_or_b32_e32 v20, 27, v183
	s_movk_i32 s6, 0x90
	v_cndmask_b32_e32 v11, 0, v231, vcc
	v_cmp_gt_u32_e32 vcc, v10, v16
	v_or_b32_e32 v186, 31, v17
	v_lshl_add_u64 v[110:111], s[2:3], 0, v[8:9]
	v_cndmask_b32_e32 v10, 0, v231, vcc
	v_cmp_gt_u32_e32 vcc, v12, v16
	v_cmp_eq_u32_e64 s[2:3], 0, v14
	v_mul_lo_u32 v14, v184, s6
	v_cndmask_b32_e32 v12, 0, v231, vcc
	v_cmp_gt_u32_e32 vcc, v13, v16
	v_mul_lo_u32 v17, v185, s6
	s_movk_i32 s6, 0x88
	v_cndmask_b32_e32 v13, 0, v231, vcc
	v_cmp_gt_u32_e32 vcc, v20, v16
	v_readlane_b32 s29, v254, 15
	v_sub_u32_e32 v9, v188, v18
	v_cndmask_b32_e32 v20, 0, v231, vcc
	v_lshlrev_b32_e32 v187, 2, v15
	v_lshlrev_b32_e32 v15, 4, v22
	v_lshlrev_b32_e32 v18, 4, v23
	v_mul_lo_u32 v4, v4, s6
	v_mul_lo_u32 v6, v6, s6
	v_lshl_add_u64 v[112:113], s[4:5], 0, v[0:1]
	v_lshl_add_u64 v[114:115], s[4:5], 0, v[2:3]
	v_mul_u32_u24_e32 v0, 0x90, v16
	v_mul_u32_u24_e32 v1, 0x88, v16
	v_mov_b32_e32 v117, 0
	s_movk_i32 s4, 0x3400
	v_perm_b32 v86, v13, v10, s0
	v_perm_b32 v85, v11, v7, s0
	v_perm_b32 v87, v20, v12, s0
	v_perm_b32 v84, v5, v19, s0
	v_mov_b32_e32 v105, v104
	v_add_u32_e32 v190, v14, v15
	v_add_u32_e32 v191, v17, v18
	v_add3_u32 v192, v8, v4, s4
	v_add3_u32 v193, v8, v6, s4
	v_add_u32_e32 v188, v188, v0
	v_add_u32_e32 v194, v9, v1
	s_mov_b32 s29, s12
	v_mov_b32_e32 v16, v117
	v_mov_b32_e32 v17, v117
	v_mov_b32_e32 v18, v117
	v_mov_b32_e32 v19, v117
	v_mov_b32_e32 v20, v117
	v_mov_b32_e32 v21, v117
	v_mov_b32_e32 v22, v117
	v_mov_b32_e32 v23, v117
	v_mov_b32_e32 v24, v117
	v_mov_b32_e32 v25, v117
	v_mov_b32_e32 v26, v117
	v_mov_b32_e32 v27, v117
	v_mov_b32_e32 v28, v117
	v_mov_b32_e32 v29, v117
	v_mov_b32_e32 v30, v117
	v_mov_b32_e32 v31, v117
	v_mov_b32_e32 v0, v117
	v_mov_b32_e32 v1, v117
	v_mov_b32_e32 v2, v117
	v_mov_b32_e32 v3, v117
	v_mov_b32_e32 v4, v117
	v_mov_b32_e32 v5, v117
	v_mov_b32_e32 v6, v117
	v_mov_b32_e32 v7, v117
	v_mov_b32_e32 v8, v117
	v_mov_b32_e32 v9, v117
	v_mov_b32_e32 v10, v117
	v_mov_b32_e32 v11, v117
	v_mov_b32_e32 v12, v117
	v_mov_b32_e32 v13, v117
	v_mov_b32_e32 v14, v117
	v_mov_b32_e32 v15, v117
	v_readlane_b32 s22, v254, 8
	v_readlane_b32 s23, v254, 9
	v_readlane_b32 s24, v254, 10
	v_readlane_b32 s25, v254, 11
	v_readlane_b32 s26, v254, 12
	v_readlane_b32 s27, v254, 13
	v_readlane_b32 s28, v254, 14
	v_readlane_b32 s30, v254, 16
	v_readlane_b32 s31, v254, 17
	s_branch .LBB0_209
